# G2 seam hooks aligned across wave halves (2 extra conditional barriers per seam) + G1b epilogue scale loads hoisted to unit start (prefetch into free VGPRs, vmcnt(0) dropped)
# speedup vs baseline: 1.0057x; 1.0057x over previous
;     __host__ __device__ bool next(int i, Unit& u) const {
;     ...
;         if (seg) { int w, base;
;             if (i < sn0) { w = sw0; base = i * sw0; } else if (i < sn0 + sn1) { w = sw1; base = sn0 * sw0 + (i - sn0) * sw1; } else if (i < sn0 + sn1 + sn2) { w = sw2; base = sn0 * sw0 + sn1 * sw1 + (i - sn0 - sn1) * sw2; } else return false;
;             if (c >= w) return false;
;             L = base + c; if (L >= nwg + nextra) return false; }
;         else if (i < full) L = (long)i * G + c;
;         else { const int idx = (i - full) * n3 + c; if (c >= n3 || idx >= rem) return false; L = (long)full * G + idx; }
;     __device__ __forceinline__ void operator()(const i32x4 (&acc)[2][2][4][2], const Unit& u, int wr, int wc, int fr, int fq) const {
;     ...
;         const int row0 = u.pm * BM + wr * 64 + fr, cw = u.pn * BM + wc * 32 + 8 * fq, col0 = cw + (gate ? (C_BF1 - C_BF0) : 0);
;         f32x4 cs[2][2];
; #pragma unroll
;         for (int bj = 0; bj < 2; ++bj)
; #pragma unroll
;             for (int n = 0; n < 2; ++n) cs[bj][n] = *(const f32x4*)(sw + cw + bj * HALF + 4 * n);
;         float rs8[2][4];
; #pragma unroll
;         for (int ai = 0; ai < 2; ++ai)
; #pragma unroll
;             for (int m = 0; m < 4; ++m) rs8[ai][m] = su[row0 + ai * HALF + m * 16];
.LBB0_305:
	s_add_i32 s96, s96, 1
	v_lshl_add_u32 v0, s40, 8, v186
	v_lshl_or_b32 v2, s4, 8, v188
	v_ashrrev_i32_e32 v1, 31, v0
	v_ashrrev_i32_e32 v3, 31, v2
	v_lshl_add_u64 v[0:1], v[0:1], 2, s[22:23]
	v_lshl_add_u64 v[2:3], v[2:3], 2, s[24:25]
	global_load_dwordx4 v[222:225], v[2:3], off offset:16
	global_load_dwordx4 v[226:229], v[2:3], off
	global_load_dwordx4 v[230:233], v[2:3], off offset:528
	global_load_dwordx4 v[242:245], v[2:3], off offset:512
	global_load_dword v241, v[0:1], off
	global_load_dword v246, v[0:1], off offset:64
	global_load_dword v247, v[0:1], off offset:128
	global_load_dword v248, v[0:1], off offset:192
	global_load_dword v249, v[0:1], off offset:512
	global_load_dword v250, v[0:1], off offset:576
	global_load_dword v251, v[0:1], off offset:640
	global_load_dword v255, v[0:1], off offset:704
	s_and_b64 vcc, exec, s[6:7]
	s_cbranch_vccz .LBB0_309
	s_cmp_ge_i32 s96, s58
	s_cbranch_scc0 .LBB0_310
	s_sub_i32 s5, s96, s58
	s_mul_i32 s5, s5, s63
	s_add_i32 s5, s5, s8
	s_cmp_lt_i32 s5, s62
	s_cselect_b64 s[34:35], -1, 0
	s_and_b64 s[34:35], s[28:29], s[34:35]
	s_mov_b64 s[36:37], 0
	s_and_b64 vcc, exec, s[34:35]
	s_mov_b64 s[34:35], 0
	s_cbranch_vccz .LBB0_311
	s_ashr_i32 s13, s5, 31
	s_add_u32 s38, s59, s5
	s_mul_hi_i32 s5, s58, s1
	s_addc_u32 s39, s5, s13
	s_mov_b64 s[34:35], -1
	s_branch .LBB0_311

;     __device__ __forceinline__ void operator()(const i32x4 (&acc)[2][2][4][2], const Unit& u, int wr, int wc, int fr, int fq) const {
;     ...
;         const int row0 = u.pm * BM + wr * 64 + fr, cw = u.pn * BM + wc * 32 + 8 * fq, col0 = cw + (gate ? (C_BF1 - C_BF0) : 0);
;         f32x4 cs[2][2];
; #pragma unroll
;         for (int bj = 0; bj < 2; ++bj)
; #pragma unroll
;             for (int n = 0; n < 2; ++n) cs[bj][n] = *(const f32x4*)(sw + cw + bj * HALF + 4 * n);
;         float rs8[2][4];
; #pragma unroll
;         for (int ai = 0; ai < 2; ++ai)
; #pragma unroll
;             for (int m = 0; m < 4; ++m) rs8[ai][m] = su[row0 + ai * HALF + m * 16];
; #pragma unroll
;         for (int ai = 0; ai < 2; ++ai)
; #pragma unroll
;             for (int m = 0; m < 4; ++m) { const int row = row0 + ai * HALF + m * 16; const float rs = rs8[ai][m]; bf16_t* rowp = O + (size_t)row * ldc + col0;
; #pragma unroll
;                 for (int bj = 0; bj < 2; ++bj) { f32x4 v0, v1;
; #pragma unroll
;                     for (int e = 0; e < 4; ++e) { v0[e] = (float)acc[ai][bj][m][0][e] * rs * cs[bj][0][e]; v1[e] = (float)acc[ai][bj][m][1][e] * rs * cs[bj][1][e]; }
.LBB0_338:
	v_lshl_add_u32 v158, s40, 8, v186
	v_lshl_or_b32 v180, s4, 8, v188
	v_or_b32_e32 v176, 16, v158
	v_or_b32_e32 v172, 32, v158
	v_or_b32_e32 v168, 48, v158
	v_ashrrev_i32_e32 v181, 31, v180
	v_ashrrev_i32_e32 v159, 31, v158
	v_ashrrev_i32_e32 v177, 31, v176
	v_ashrrev_i32_e32 v173, 31, v172
	v_ashrrev_i32_e32 v169, 31, v168
	v_mov_b64_e32 v[64:65], v[222:223]
	v_mov_b64_e32 v[66:67], v[224:225]
	v_mov_b64_e32 v[68:69], v[226:227]
	v_mov_b64_e32 v[70:71], v[228:229]
	v_mov_b64_e32 v[48:49], v[230:231]
	v_mov_b64_e32 v[50:51], v[232:233]
	v_mov_b64_e32 v[52:53], v[242:243]
	v_mov_b64_e32 v[54:55], v[244:245]
	v_cvt_f32_i32_e32 v143, v143
	v_mov_b32_e32 v178, v241
	v_mov_b32_e32 v174, v246
	v_mov_b32_e32 v170, v247
	v_mov_b32_e32 v166, v248
	v_mov_b32_e32 v164, v249
	v_mov_b32_e32 v162, v250
	v_mov_b32_e32 v160, v251
	v_mov_b32_e32 v156, v255
	v_cvt_f32_i32_e32 v142, v142
	v_cvt_f32_i32_e32 v139, v139
	v_cvt_f32_i32_e32 v138, v138
	v_cvt_f32_i32_e32 v145, v145
	v_cvt_f32_i32_e32 v144, v144
	v_cvt_f32_i32_e32 v141, v141
	v_cvt_f32_i32_e32 v140, v140
	s_cmp_gt_i32 s4, 19
	s_cselect_b64 s[46:47], -1, 0
	s_cmp_lt_i32 s4, 20
	s_mov_b64 s[54:55], -1
	s_cselect_b64 s[40:41], -1, 0
	s_and_b64 vcc, exec, s[46:47]
	v_pk_mul_f32 v[142:143], v[178:179], v[142:143] op_sel_hi:[0,1]
	v_pk_mul_f32 v[138:139], v[178:179], v[138:139] op_sel_hi:[0,1]
	v_pk_mul_f32 v[144:145], v[178:179], v[144:145] op_sel_hi:[0,1]
	v_pk_mul_f32 v[140:141], v[178:179], v[140:141] op_sel_hi:[0,1]
	v_pk_mul_f32 v[182:183], v[68:69], v[142:143]
	v_pk_mul_f32 v[142:143], v[64:65], v[138:139]
	v_pk_mul_f32 v[184:185], v[70:71], v[144:145]
	v_pk_mul_f32 v[144:145], v[66:67], v[140:141]
	s_cbranch_vccnz .LBB0_340
	s_mov_b64 s[54:55], 0

; __device__ __forceinline__ float bf_lo(unsigned w) { return __uint_as_float(w << 16); }
; __device__ __forceinline__ float bf_hi(unsigned w) { return __uint_as_float(w & 0xffff0000u); }
;     __device__ __forceinline__ void seam_mul(f32x4 (&acc)[2][2][4][2], int ai, int m, int bj, const u32x4 a, const u32x4 b) const {
;         f32x4 r0, r1;
;         r0[0] = bf_lo(a.x) * __builtin_amdgcn_rcpf(fmaxf(bf_lo(b.x), 1e-6f)); r0[1] = bf_hi(a.x) * __builtin_amdgcn_rcpf(fmaxf(bf_hi(b.x), 1e-6f));
;         r0[2] = bf_lo(a.y) * __builtin_amdgcn_rcpf(fmaxf(bf_lo(b.y), 1e-6f)); r0[3] = bf_hi(a.y) * __builtin_amdgcn_rcpf(fmaxf(bf_hi(b.y), 1e-6f));
;         r1[0] = bf_lo(a.z) * __builtin_amdgcn_rcpf(fmaxf(bf_lo(b.z), 1e-6f)); r1[1] = bf_hi(a.z) * __builtin_amdgcn_rcpf(fmaxf(bf_hi(b.z), 1e-6f));
;         r1[2] = bf_lo(a.w) * __builtin_amdgcn_rcpf(fmaxf(bf_lo(b.w), 1e-6f)); r1[3] = bf_hi(a.w) * __builtin_amdgcn_rcpf(fmaxf(bf_hi(b.w), 1e-6f));
;         acc[ai][bj][m][0] *= r0; acc[ai][bj][m][1] *= r1;
;     }
;     __device__ __forceinline__ void mid(f32x4 (&acc)[2][2][4][2], const Unit& u, int seg, int wr, int wc, int fr, int fq) const {
;         asm volatile("" : "+v"(fr), "+v"(fq));
;         const int row0 = u.pm * BM + wr * 64 + fr, col0 = u.pn * BM + wc * 32 + 8 * fq;
;         u32x4 ga[4][2], gb[4][2], ha[4][2], hb[4][2];
; #pragma unroll
;         for (int m = 0; m < 4; ++m) { const bf16_t* gp = gate + (size_t)(row0 + m * 16) * ldg + seg * DM + col0;
; #pragma unroll
;             for (int bj = 0; bj < 2; ++bj) { ga[m][bj] = *(const u32x4*)(gp + bj * HALF); gb[m][bj] = *(const u32x4*)(gp + DM + bj * HALF); } }
; #pragma unroll
;         for (int m = 0; m < 4; ++m) {
; #pragma unroll
;             for (int bj = 0; bj < 2; ++bj) seam_mul(acc, 0, m, bj, ga[m][bj], gb[m][bj]);
;             const bf16_t* gp = gate + (size_t)(row0 + HALF + m * 16) * ldg + seg * DM + col0;
; #pragma unroll
;             for (int bj = 0; bj < 2; ++bj) { ha[m][bj] = *(const u32x4*)(gp + bj * HALF); hb[m][bj] = *(const u32x4*)(gp + DM + bj * HALF); } }
.LBB0_711:
	s_andn2_b64 vcc, exec, s[56:57]
	s_cbranch_vccnz .LBB0_713
	s_and_b64 vcc, exec, s[28:29]
	s_cbranch_vccz .Lmid_nb1
	s_barrier
.Lmid_nb1:
	v_mov_b32_e32 v96, v218
	v_mov_b32_e32 v98, v219
	s_cmpk_eq_i32 s54, 0xf00
	s_cselect_b32 s16, 0, 0x2000
	v_lshl_add_u32 v98, v98, 3, s76
	s_add_u32 s56, s20, s16
	v_ashrrev_i32_e32 v99, 31, v98
	s_addc_u32 s57, s21, 0
	v_lshlrev_b64 v[98:99], 1, v[98:99]
	v_add_u32_e32 v96, s39, v96
	v_lshl_add_u64 v[132:133], s[56:57], 0, v[98:99]
	v_mad_i64_i32 v[134:135], s[56:57], v96, s64, v[132:133]
	global_load_dwordx4 v[180:183], v[134:135], off
	v_add_co_u32_e32 v136, vcc, s33, v134
	v_add_u32_e32 v225, 0x80, v96
	s_nop 0
	v_addc_co_u32_e32 v137, vcc, 0, v135, vcc
	global_load_dwordx4 v[188:191], v[136:137], off
	global_load_dwordx4 v[164:167], v[134:135], off offset:256
	global_load_dwordx4 v[172:175], v[136:137], off offset:256
	v_add_u32_e32 v134, 16, v96
	v_mad_i64_i32 v[134:135], s[56:57], v134, s64, v[132:133]
	global_load_dwordx4 v[184:187], v[134:135], off
	v_add_co_u32_e32 v136, vcc, s33, v134
	s_waitcnt vmcnt(0)
	v_lshlrev_b32_e32 v226, 16, v180
	v_addc_co_u32_e32 v137, vcc, 0, v135, vcc
	global_load_dwordx4 v[192:195], v[136:137], off
	global_load_dwordx4 v[168:171], v[134:135], off offset:256
	global_load_dwordx4 v[176:179], v[136:137], off offset:256
	v_add_u32_e32 v134, 32, v96
	v_mad_i64_i32 v[134:135], s[56:57], v134, s64, v[132:133]
	global_load_dwordx4 v[156:159], v[134:135], off
	v_add_co_u32_e32 v136, vcc, s33, v134
	v_lshlrev_b32_e32 v216, 16, v188
	s_nop 0
	v_addc_co_u32_e32 v137, vcc, 0, v135, vcc
	global_load_dwordx4 v[160:163], v[136:137], off
	global_load_dwordx4 v[148:151], v[134:135], off offset:256
	global_load_dwordx4 v[152:155], v[136:137], off offset:256
	v_add_u32_e32 v134, 48, v96
	v_mad_i64_i32 v[132:133], s[56:57], v134, s64, v[132:133]
	v_and_b32_e32 v188, 0xffff0000, v188
	v_and_b32_e32 v227, 0xffff0000, v180
	v_lshlrev_b32_e32 v180, 16, v189
	global_load_dwordx4 v[140:143], v[132:133], off
	v_add_co_u32_e32 v136, vcc, s33, v132
	v_max_f32_e32 v216, v216, v216
	v_max_f32_e32 v188, v188, v188
	v_max_f32_e32 v180, v180, v180
	v_addc_co_u32_e32 v137, vcc, 0, v133, vcc
	v_max_f32_e32 v216, 0x358637bd, v216
	v_max_f32_e32 v188, 0x358637bd, v188
	v_max_f32_e32 v180, 0x358637bd, v180
	global_load_dwordx4 v[144:147], v[136:137], off
	s_nop 0
	global_load_dwordx4 v[132:135], v[132:133], off offset:256
	s_nop 0
	global_load_dwordx4 v[136:139], v[136:137], off offset:256
	v_rcp_f32_e32 v216, v216
	v_rcp_f32_e32 v217, v188
	v_rcp_f32_e32 v188, v180
	v_and_b32_e32 v180, 0xffff0000, v189
	v_max_f32_e32 v180, v180, v180
	v_max_f32_e32 v180, 0x358637bd, v180
	v_rcp_f32_e32 v189, v180
	v_pk_mul_f32 v[216:217], v[216:217], v[226:227]
	v_lshlrev_b32_e32 v226, 16, v182
	v_and_b32_e32 v227, 0xffff0000, v182
	v_lshlrev_b32_e32 v182, 16, v191
	v_max_f32_e32 v182, v182, v182
	v_lshlrev_b32_e32 v180, 16, v181
	v_and_b32_e32 v181, 0xffff0000, v181
	v_max_f32_e32 v182, 0x358637bd, v182
	v_pk_mul_f32 v[180:181], v[188:189], v[180:181]
	v_lshlrev_b32_e32 v188, 16, v190
	v_and_b32_e32 v189, 0xffff0000, v190
	v_rcp_f32_e32 v190, v182
	v_and_b32_e32 v182, 0xffff0000, v191
	v_max_f32_e32 v182, v182, v182
	v_max_f32_e32 v182, 0x358637bd, v182
	v_rcp_f32_e32 v191, v182
	v_lshlrev_b32_e32 v182, 16, v183
	v_and_b32_e32 v183, 0xffff0000, v183
	v_pk_mul_f32 v[130:131], v[130:131], v[180:181]
	v_pk_mul_f32 v[182:183], v[190:191], v[182:183]
	v_lshlrev_b32_e32 v180, 16, v172
	v_pk_mul_f32 v[126:127], v[126:127], v[182:183]
	v_and_b32_e32 v172, 0xffff0000, v172
	v_lshlrev_b32_e32 v182, 16, v164
	v_and_b32_e32 v183, 0xffff0000, v164
	v_lshlrev_b32_e32 v164, 16, v173
	v_max_f32_e32 v172, v172, v172
	v_max_f32_e32 v164, v164, v164
	v_max_f32_e32 v172, 0x358637bd, v172
	v_max_f32_e32 v164, 0x358637bd, v164
	v_max_f32_e32 v180, v180, v180
	v_rcp_f32_e32 v181, v172
	v_rcp_f32_e32 v172, v164
	v_and_b32_e32 v164, 0xffff0000, v173
	v_max_f32_e32 v180, 0x358637bd, v180
	v_max_f32_e32 v164, v164, v164
	v_rcp_f32_e32 v180, v180
	v_max_f32_e32 v164, 0x358637bd, v164
	v_rcp_f32_e32 v173, v164
	v_lshlrev_b32_e32 v164, 16, v165
	v_pk_mul_f32 v[180:181], v[180:181], v[182:183]
	v_and_b32_e32 v165, 0xffff0000, v165
	v_lshlrev_b32_e32 v182, 16, v166
	v_and_b32_e32 v183, 0xffff0000, v166
	v_lshlrev_b32_e32 v166, 16, v175
	v_pk_mul_f32 v[164:165], v[172:173], v[164:165]
	v_lshlrev_b32_e32 v172, 16, v174
	v_and_b32_e32 v173, 0xffff0000, v174
	v_max_f32_e32 v166, v166, v166
	v_max_f32_e32 v172, v172, v172
	v_max_f32_e32 v173, v173, v173
	v_max_f32_e32 v166, 0x358637bd, v166
	v_max_f32_e32 v172, 0x358637bd, v172
	v_max_f32_e32 v173, 0x358637bd, v173
	v_rcp_f32_e32 v174, v166
	v_and_b32_e32 v166, 0xffff0000, v175
	v_max_f32_e32 v188, v188, v188
	v_max_f32_e32 v189, v189, v189
	v_rcp_f32_e32 v172, v172
	v_rcp_f32_e32 v173, v173
	v_max_f32_e32 v166, v166, v166
	v_max_f32_e32 v188, 0x358637bd, v188
	v_max_f32_e32 v189, 0x358637bd, v189
	v_pk_mul_f32 v[128:129], v[128:129], v[216:217]
	v_max_f32_e32 v166, 0x358637bd, v166
	v_mov_b64_e32 v[216:217], s[20:21]
	v_rcp_f32_e32 v188, v188
	v_rcp_f32_e32 v189, v189
	v_rcp_f32_e32 v175, v166
	v_pk_mul_f32 v[122:123], v[122:123], v[164:165]
	v_mad_i64_i32 v[164:165], s[56:57], v225, s64, v[216:217]
	v_lshl_add_u64 v[164:165], v[164:165], 0, s[16:17]
	v_pk_mul_f32 v[172:173], v[172:173], v[182:183]
	v_lshl_add_u64 v[164:165], v[164:165], 0, v[98:99]
	v_lshlrev_b32_e32 v166, 16, v167
	v_and_b32_e32 v167, 0xffff0000, v167
	v_pk_mul_f32 v[116:117], v[116:117], v[172:173]
	v_add_co_u32_e32 v172, vcc, s33, v164
	v_pk_mul_f32 v[188:189], v[188:189], v[226:227]
	v_pk_mul_f32 v[166:167], v[174:175], v[166:167]
	v_addc_co_u32_e32 v173, vcc, 0, v165, vcc
	v_pk_mul_f32 v[124:125], v[124:125], v[188:189]
	v_pk_mul_f32 v[120:121], v[120:121], v[180:181]
	v_pk_mul_f32 v[118:119], v[118:119], v[166:167]
	global_load_dwordx4 v[180:183], v[164:165], off
	global_load_dwordx4 v[188:191], v[172:173], off
	s_nop 0
	global_load_dwordx4 v[164:167], v[164:165], off offset:256
	s_nop 0
	global_load_dwordx4 v[172:175], v[172:173], off offset:256
	s_waitcnt vmcnt(14)
; __device__ __forceinline__ float bf_lo(unsigned w) { return __uint_as_float(w << 16); }
; __device__ __forceinline__ float bf_hi(unsigned w) { return __uint_as_float(w & 0xffff0000u); }
;     __device__ __forceinline__ void seam_mul(f32x4 (&acc)[2][2][4][2], int ai, int m, int bj, const u32x4 a, const u32x4 b) const {
;         f32x4 r0, r1;
;         r0[0] = bf_lo(a.x) * __builtin_amdgcn_rcpf(fmaxf(bf_lo(b.x), 1e-6f)); r0[1] = bf_hi(a.x) * __builtin_amdgcn_rcpf(fmaxf(bf_hi(b.x), 1e-6f));
;         r0[2] = bf_lo(a.y) * __builtin_amdgcn_rcpf(fmaxf(bf_lo(b.y), 1e-6f)); r0[3] = bf_hi(a.y) * __builtin_amdgcn_rcpf(fmaxf(bf_hi(b.y), 1e-6f));
;         r1[0] = bf_lo(a.z) * __builtin_amdgcn_rcpf(fmaxf(bf_lo(b.z), 1e-6f)); r1[1] = bf_hi(a.z) * __builtin_amdgcn_rcpf(fmaxf(bf_hi(b.z), 1e-6f));
;         r1[2] = bf_lo(a.w) * __builtin_amdgcn_rcpf(fmaxf(bf_lo(b.w), 1e-6f)); r1[3] = bf_hi(a.w) * __builtin_amdgcn_rcpf(fmaxf(bf_hi(b.w), 1e-6f));
;         acc[ai][bj][m][0] *= r0; acc[ai][bj][m][1] *= r1;
;     __device__ __forceinline__ void mid(f32x4 (&acc)[2][2][4][2], const Unit& u, int seg, int wr, int wc, int fr, int fq) const {
;     ...
;         for (int m = 0; m < 4; ++m) {
; #pragma unroll
;             for (int bj = 0; bj < 2; ++bj) seam_mul(acc, 0, m, bj, ga[m][bj], gb[m][bj]);
;             const bf16_t* gp = gate + (size_t)(row0 + HALF + m * 16) * ldg + seg * DM + col0;
; #pragma unroll
;             for (int bj = 0; bj < 2; ++bj) { ha[m][bj] = *(const u32x4*)(gp + bj * HALF); hb[m][bj] = *(const u32x4*)(gp + DM + bj * HALF); } }
	v_lshlrev_b32_e32 v225, 16, v192
	v_and_b32_e32 v192, 0xffff0000, v192
	v_lshlrev_b32_e32 v228, 16, v184
	v_and_b32_e32 v229, 0xffff0000, v184
	v_lshlrev_b32_e32 v184, 16, v193
	v_max_f32_e32 v192, v192, v192
	v_max_f32_e32 v184, v184, v184
	v_max_f32_e32 v192, 0x358637bd, v192
	v_max_f32_e32 v184, 0x358637bd, v184
	v_rcp_f32_e32 v227, v192
	v_rcp_f32_e32 v192, v184
	v_and_b32_e32 v184, 0xffff0000, v193
	v_max_f32_e32 v225, v225, v225
	v_max_f32_e32 v184, v184, v184
	v_max_f32_e32 v225, 0x358637bd, v225
	v_max_f32_e32 v184, 0x358637bd, v184
	v_rcp_f32_e32 v226, v225
	v_rcp_f32_e32 v193, v184
	v_lshlrev_b32_e32 v184, 16, v185
	v_and_b32_e32 v185, 0xffff0000, v185
	v_pk_mul_f32 v[226:227], v[226:227], v[228:229]
	v_pk_mul_f32 v[184:185], v[192:193], v[184:185]
	v_lshlrev_b32_e32 v192, 16, v194
	v_and_b32_e32 v193, 0xffff0000, v194
	v_lshlrev_b32_e32 v228, 16, v186
	v_and_b32_e32 v229, 0xffff0000, v186
	v_lshlrev_b32_e32 v186, 16, v195
	v_max_f32_e32 v192, v192, v192
	v_max_f32_e32 v193, v193, v193
	v_max_f32_e32 v186, v186, v186
	v_max_f32_e32 v192, 0x358637bd, v192
	v_max_f32_e32 v193, 0x358637bd, v193
	v_max_f32_e32 v186, 0x358637bd, v186
	v_rcp_f32_e32 v192, v192
	v_rcp_f32_e32 v193, v193
	v_rcp_f32_e32 v194, v186
	v_and_b32_e32 v186, 0xffff0000, v195
	v_max_f32_e32 v186, v186, v186
	v_max_f32_e32 v186, 0x358637bd, v186
	v_rcp_f32_e32 v195, v186
	v_pk_mul_f32 v[192:193], v[192:193], v[228:229]
	s_waitcnt vmcnt(10)
	v_lshlrev_b32_e32 v225, 16, v160
	v_and_b32_e32 v160, 0xffff0000, v160
	v_lshlrev_b32_e32 v228, 16, v156
	v_and_b32_e32 v229, 0xffff0000, v156
	v_lshlrev_b32_e32 v156, 16, v161
	v_max_f32_e32 v160, v160, v160
	v_max_f32_e32 v156, v156, v156
	v_lshlrev_b32_e32 v186, 16, v187
	v_and_b32_e32 v187, 0xffff0000, v187
	v_max_f32_e32 v160, 0x358637bd, v160
	v_max_f32_e32 v156, 0x358637bd, v156
	v_pk_mul_f32 v[186:187], v[194:195], v[186:187]
	v_pk_mul_f32 v[112:113], v[112:113], v[226:227]
	v_rcp_f32_e32 v227, v160
	v_rcp_f32_e32 v160, v156
	v_and_b32_e32 v156, 0xffff0000, v161
	v_pk_mul_f32 v[114:115], v[114:115], v[184:185]
	v_pk_mul_f32 v[110:111], v[110:111], v[186:187]
	v_lshlrev_b32_e32 v184, 16, v176
	v_and_b32_e32 v176, 0xffff0000, v176
	v_lshlrev_b32_e32 v186, 16, v168
	v_and_b32_e32 v187, 0xffff0000, v168
	v_lshlrev_b32_e32 v168, 16, v177
	v_max_f32_e32 v156, v156, v156
	v_max_f32_e32 v176, v176, v176
	v_max_f32_e32 v168, v168, v168
	v_max_f32_e32 v156, 0x358637bd, v156
	v_max_f32_e32 v176, 0x358637bd, v176
	v_max_f32_e32 v168, 0x358637bd, v168
	v_rcp_f32_e32 v161, v156
	v_max_f32_e32 v184, v184, v184
	v_rcp_f32_e32 v185, v176
	v_rcp_f32_e32 v176, v168
	v_and_b32_e32 v168, 0xffff0000, v177
	v_max_f32_e32 v184, 0x358637bd, v184
	v_max_f32_e32 v168, v168, v168
	v_rcp_f32_e32 v184, v184
	v_max_f32_e32 v168, 0x358637bd, v168
	v_lshlrev_b32_e32 v156, 16, v157
	v_and_b32_e32 v157, 0xffff0000, v157
	v_rcp_f32_e32 v177, v168
	v_max_f32_e32 v225, v225, v225
	v_pk_mul_f32 v[156:157], v[160:161], v[156:157]
	v_lshlrev_b32_e32 v160, 16, v162
	v_and_b32_e32 v161, 0xffff0000, v162
	v_max_f32_e32 v225, 0x358637bd, v225
	v_max_f32_e32 v160, v160, v160
	v_max_f32_e32 v161, v161, v161
	v_rcp_f32_e32 v226, v225
	v_max_f32_e32 v160, 0x358637bd, v160
	v_max_f32_e32 v161, 0x358637bd, v161
	v_pk_mul_f32 v[184:185], v[184:185], v[186:187]
	v_lshlrev_b32_e32 v168, 16, v169
	v_and_b32_e32 v169, 0xffff0000, v169
	v_lshlrev_b32_e32 v186, 16, v170
	v_and_b32_e32 v187, 0xffff0000, v170
	v_lshlrev_b32_e32 v170, 16, v179
	v_rcp_f32_e32 v160, v160
	v_rcp_f32_e32 v161, v161
	v_pk_mul_f32 v[168:169], v[176:177], v[168:169]
	v_lshlrev_b32_e32 v176, 16, v178
	v_and_b32_e32 v177, 0xffff0000, v178
	v_max_f32_e32 v170, v170, v170
	v_max_f32_e32 v176, v176, v176
	v_max_f32_e32 v177, v177, v177
	v_max_f32_e32 v170, 0x358637bd, v170
	v_max_f32_e32 v176, 0x358637bd, v176
	v_max_f32_e32 v177, 0x358637bd, v177
	v_rcp_f32_e32 v178, v170
	v_and_b32_e32 v170, 0xffff0000, v179
	v_pk_mul_f32 v[226:227], v[226:227], v[228:229]
	v_lshlrev_b32_e32 v228, 16, v158
	v_and_b32_e32 v229, 0xffff0000, v158
	v_rcp_f32_e32 v176, v176
	v_rcp_f32_e32 v177, v177
	v_max_f32_e32 v170, v170, v170
	v_pk_mul_f32 v[160:161], v[160:161], v[228:229]
	s_waitcnt vmcnt(6)
	v_lshlrev_b32_e32 v225, 16, v144
	v_and_b32_e32 v144, 0xffff0000, v144
	v_lshlrev_b32_e32 v228, 16, v140
	v_and_b32_e32 v229, 0xffff0000, v140
	v_lshlrev_b32_e32 v140, 16, v145
	v_max_f32_e32 v170, 0x358637bd, v170
	v_pk_mul_f32 v[106:107], v[106:107], v[168:169]
	v_add_u32_e32 v168, 0x90, v96
	v_max_f32_e32 v225, v225, v225
	v_max_f32_e32 v144, v144, v144
	v_max_f32_e32 v140, v140, v140
	v_rcp_f32_e32 v179, v170
	v_mad_i64_i32 v[168:169], s[56:57], v168, s64, v[216:217]
	v_max_f32_e32 v225, 0x358637bd, v225
	v_max_f32_e32 v144, 0x358637bd, v144
	v_max_f32_e32 v140, 0x358637bd, v140
	v_lshl_add_u64 v[168:169], v[168:169], 0, s[16:17]
	v_pk_mul_f32 v[92:93], v[92:93], v[226:227]
	v_rcp_f32_e32 v226, v225
	v_rcp_f32_e32 v227, v144
	v_rcp_f32_e32 v144, v140
	v_and_b32_e32 v140, 0xffff0000, v145
	v_pk_mul_f32 v[176:177], v[176:177], v[186:187]
	v_lshl_add_u64 v[168:169], v[168:169], 0, v[98:99]
	v_max_f32_e32 v140, v140, v140
	v_lshlrev_b32_e32 v170, 16, v171
	v_and_b32_e32 v171, 0xffff0000, v171
	v_pk_mul_f32 v[100:101], v[100:101], v[176:177]
	v_add_co_u32_e32 v176, vcc, s33, v168
	v_lshlrev_b32_e32 v158, 16, v163
	v_max_f32_e32 v140, 0x358637bd, v140
	v_pk_mul_f32 v[170:171], v[178:179], v[170:171]
	v_addc_co_u32_e32 v177, vcc, 0, v169, vcc
	v_max_f32_e32 v158, v158, v158
	v_rcp_f32_e32 v145, v140
	v_pk_mul_f32 v[108:109], v[108:109], v[192:193]
	v_pk_mul_f32 v[104:105], v[104:105], v[184:185]
	v_pk_mul_f32 v[102:103], v[102:103], v[170:171]
; __device__ __forceinline__ float bf_lo(unsigned w) { return __uint_as_float(w << 16); }
; __device__ __forceinline__ float bf_hi(unsigned w) { return __uint_as_float(w & 0xffff0000u); }
;     __device__ __forceinline__ void seam_mul(f32x4 (&acc)[2][2][4][2], int ai, int m, int bj, const u32x4 a, const u32x4 b) const {
;         f32x4 r0, r1;
;         r0[0] = bf_lo(a.x) * __builtin_amdgcn_rcpf(fmaxf(bf_lo(b.x), 1e-6f)); r0[1] = bf_hi(a.x) * __builtin_amdgcn_rcpf(fmaxf(bf_hi(b.x), 1e-6f));
;         r0[2] = bf_lo(a.y) * __builtin_amdgcn_rcpf(fmaxf(bf_lo(b.y), 1e-6f)); r0[3] = bf_hi(a.y) * __builtin_amdgcn_rcpf(fmaxf(bf_hi(b.y), 1e-6f));
;         r1[0] = bf_lo(a.z) * __builtin_amdgcn_rcpf(fmaxf(bf_lo(b.z), 1e-6f)); r1[1] = bf_hi(a.z) * __builtin_amdgcn_rcpf(fmaxf(bf_hi(b.z), 1e-6f));
;         r1[2] = bf_lo(a.w) * __builtin_amdgcn_rcpf(fmaxf(bf_lo(b.w), 1e-6f)); r1[3] = bf_hi(a.w) * __builtin_amdgcn_rcpf(fmaxf(bf_hi(b.w), 1e-6f));
;         acc[ai][bj][m][0] *= r0; acc[ai][bj][m][1] *= r1;
;     __device__ __forceinline__ void mid(f32x4 (&acc)[2][2][4][2], const Unit& u, int seg, int wr, int wc, int fr, int fq) const {
;     ...
;         for (int m = 0; m < 4; ++m) {
; #pragma unroll
;             for (int bj = 0; bj < 2; ++bj) seam_mul(acc, 0, m, bj, ga[m][bj], gb[m][bj]);
;             const bf16_t* gp = gate + (size_t)(row0 + HALF + m * 16) * ldg + seg * DM + col0;
; #pragma unroll
;             for (int bj = 0; bj < 2; ++bj) { ha[m][bj] = *(const u32x4*)(gp + bj * HALF); hb[m][bj] = *(const u32x4*)(gp + DM + bj * HALF); } }
	global_load_dwordx4 v[184:187], v[168:169], off
	global_load_dwordx4 v[192:195], v[176:177], off
	s_nop 0
	global_load_dwordx4 v[168:171], v[168:169], off offset:256
	s_nop 0
	global_load_dwordx4 v[176:179], v[176:177], off offset:256
	v_max_f32_e32 v158, 0x358637bd, v158
	v_pk_mul_f32 v[226:227], v[226:227], v[228:229]
	v_lshlrev_b32_e32 v228, 16, v142
	v_and_b32_e32 v229, 0xffff0000, v142
	v_lshlrev_b32_e32 v142, 16, v147
	v_rcp_f32_e32 v162, v158
	v_and_b32_e32 v158, 0xffff0000, v163
	v_max_f32_e32 v142, v142, v142
	v_max_f32_e32 v158, v158, v158
	v_lshlrev_b32_e32 v140, 16, v141
	v_and_b32_e32 v141, 0xffff0000, v141
	v_max_f32_e32 v142, 0x358637bd, v142
	v_max_f32_e32 v158, 0x358637bd, v158
	v_pk_mul_f32 v[140:141], v[144:145], v[140:141]
	v_lshlrev_b32_e32 v144, 16, v146
	v_and_b32_e32 v145, 0xffff0000, v146
	v_rcp_f32_e32 v146, v142
	v_and_b32_e32 v142, 0xffff0000, v147
	v_rcp_f32_e32 v163, v158
	v_max_f32_e32 v142, v142, v142
	v_max_f32_e32 v142, 0x358637bd, v142
	v_rcp_f32_e32 v147, v142
	v_lshlrev_b32_e32 v158, 16, v159
	v_and_b32_e32 v159, 0xffff0000, v159
	v_pk_mul_f32 v[158:159], v[162:163], v[158:159]
	v_pk_mul_f32 v[94:95], v[94:95], v[156:157]
	v_pk_mul_f32 v[90:91], v[90:91], v[158:159]
	v_lshlrev_b32_e32 v156, 16, v152
	v_and_b32_e32 v152, 0xffff0000, v152
	v_lshlrev_b32_e32 v158, 16, v148
	v_and_b32_e32 v159, 0xffff0000, v148
	v_lshlrev_b32_e32 v148, 16, v153
	v_lshlrev_b32_e32 v142, 16, v143
	v_and_b32_e32 v143, 0xffff0000, v143
	v_max_f32_e32 v152, v152, v152
	v_max_f32_e32 v148, v148, v148
	v_pk_mul_f32 v[142:143], v[146:147], v[142:143]
	v_max_f32_e32 v152, 0x358637bd, v152
	v_max_f32_e32 v148, 0x358637bd, v148
	v_pk_mul_f32 v[78:79], v[78:79], v[140:141]
	v_pk_mul_f32 v[74:75], v[74:75], v[142:143]
	s_waitcnt vmcnt(8)
	v_lshlrev_b32_e32 v140, 16, v136
	v_and_b32_e32 v136, 0xffff0000, v136
	v_lshlrev_b32_e32 v142, 16, v132
	v_and_b32_e32 v143, 0xffff0000, v132
	v_lshlrev_b32_e32 v132, 16, v137
	v_rcp_f32_e32 v157, v152
	v_rcp_f32_e32 v152, v148
	v_and_b32_e32 v148, 0xffff0000, v153
	v_max_f32_e32 v136, v136, v136
	v_max_f32_e32 v132, v132, v132
	v_max_f32_e32 v148, v148, v148
	v_max_f32_e32 v136, 0x358637bd, v136
	v_max_f32_e32 v132, 0x358637bd, v132
	v_max_f32_e32 v156, v156, v156
	v_max_f32_e32 v148, 0x358637bd, v148
	v_max_f32_e32 v140, v140, v140
	v_rcp_f32_e32 v141, v136
	v_rcp_f32_e32 v136, v132
	v_and_b32_e32 v132, 0xffff0000, v137
	v_max_f32_e32 v156, 0x358637bd, v156
	v_rcp_f32_e32 v153, v148
	v_max_f32_e32 v140, 0x358637bd, v140
	v_max_f32_e32 v132, v132, v132
	v_rcp_f32_e32 v156, v156
	v_rcp_f32_e32 v140, v140
	v_max_f32_e32 v132, 0x358637bd, v132
	v_rcp_f32_e32 v137, v132
	v_lshlrev_b32_e32 v148, 16, v149
	v_and_b32_e32 v149, 0xffff0000, v149
	v_pk_mul_f32 v[148:149], v[152:153], v[148:149]
	v_lshlrev_b32_e32 v152, 16, v154
	v_and_b32_e32 v153, 0xffff0000, v154
	v_pk_mul_f32 v[156:157], v[156:157], v[158:159]
	v_max_f32_e32 v152, v152, v152
	v_max_f32_e32 v153, v153, v153
	v_lshlrev_b32_e32 v158, 16, v150
	v_and_b32_e32 v159, 0xffff0000, v150
	v_lshlrev_b32_e32 v150, 16, v155
	v_pk_mul_f32 v[140:141], v[140:141], v[142:143]
	v_lshlrev_b32_e32 v132, 16, v133
	v_and_b32_e32 v133, 0xffff0000, v133
	v_lshlrev_b32_e32 v142, 16, v134
	v_and_b32_e32 v143, 0xffff0000, v134
	v_lshlrev_b32_e32 v134, 16, v139
	v_max_f32_e32 v152, 0x358637bd, v152
	v_max_f32_e32 v153, 0x358637bd, v153
	v_max_f32_e32 v150, v150, v150
	v_pk_mul_f32 v[132:133], v[136:137], v[132:133]
	v_lshlrev_b32_e32 v136, 16, v138
	v_and_b32_e32 v137, 0xffff0000, v138
	v_max_f32_e32 v134, v134, v134
	v_rcp_f32_e32 v152, v152
	v_rcp_f32_e32 v153, v153
	v_max_f32_e32 v150, 0x358637bd, v150
	v_max_f32_e32 v136, v136, v136
	v_max_f32_e32 v137, v137, v137
	v_max_f32_e32 v134, 0x358637bd, v134
	v_rcp_f32_e32 v154, v150
	v_and_b32_e32 v150, 0xffff0000, v155
	v_pk_mul_f32 v[86:87], v[86:87], v[148:149]
	v_add_u32_e32 v148, 0xa0, v96
	v_max_f32_e32 v136, 0x358637bd, v136
	v_max_f32_e32 v137, 0x358637bd, v137
	v_rcp_f32_e32 v138, v134
	v_and_b32_e32 v134, 0xffff0000, v139
	v_max_f32_e32 v150, v150, v150
	v_mad_i64_i32 v[148:149], s[56:57], v148, s64, v[216:217]
	v_max_f32_e32 v144, v144, v144
	v_max_f32_e32 v145, v145, v145
	v_rcp_f32_e32 v136, v136
	v_rcp_f32_e32 v137, v137
	v_max_f32_e32 v134, v134, v134
	v_max_f32_e32 v150, 0x358637bd, v150
	v_lshl_add_u64 v[148:149], v[148:149], 0, s[16:17]
	v_max_f32_e32 v144, 0x358637bd, v144
	v_max_f32_e32 v145, 0x358637bd, v145
	v_max_f32_e32 v134, 0x358637bd, v134
	v_add_u32_e32 v96, 0xb0, v96
	v_pk_mul_f32 v[152:153], v[152:153], v[158:159]
	v_rcp_f32_e32 v155, v150
	v_lshl_add_u64 v[148:149], v[148:149], 0, v[98:99]
	v_rcp_f32_e32 v144, v144
	v_rcp_f32_e32 v145, v145
	v_rcp_f32_e32 v139, v134
	v_pk_mul_f32 v[70:71], v[70:71], v[132:133]
	v_mad_i64_i32 v[132:133], s[56:57], v96, s64, v[216:217]
	v_pk_mul_f32 v[80:81], v[80:81], v[152:153]
	v_add_co_u32_e32 v152, vcc, s33, v148
	v_lshl_add_u64 v[132:133], v[132:133], 0, s[16:17]
	s_nop 0
	v_addc_co_u32_e32 v153, vcc, 0, v149, vcc
	v_pk_mul_f32 v[136:137], v[136:137], v[142:143]
	v_lshl_add_u64 v[98:99], v[132:133], 0, v[98:99]
	s_waitcnt vmcnt(6)
; __device__ __forceinline__ float bf_lo(unsigned w) { return __uint_as_float(w << 16); }
; __device__ __forceinline__ float bf_hi(unsigned w) { return __uint_as_float(w & 0xffff0000u); }
;     __device__ __forceinline__ void seam_mul(f32x4 (&acc)[2][2][4][2], int ai, int m, int bj, const u32x4 a, const u32x4 b) const {
;         f32x4 r0, r1;
;         r0[0] = bf_lo(a.x) * __builtin_amdgcn_rcpf(fmaxf(bf_lo(b.x), 1e-6f)); r0[1] = bf_hi(a.x) * __builtin_amdgcn_rcpf(fmaxf(bf_hi(b.x), 1e-6f));
;         r0[2] = bf_lo(a.y) * __builtin_amdgcn_rcpf(fmaxf(bf_lo(b.y), 1e-6f)); r0[3] = bf_hi(a.y) * __builtin_amdgcn_rcpf(fmaxf(bf_hi(b.y), 1e-6f));
;         r1[0] = bf_lo(a.z) * __builtin_amdgcn_rcpf(fmaxf(bf_lo(b.z), 1e-6f)); r1[1] = bf_hi(a.z) * __builtin_amdgcn_rcpf(fmaxf(bf_hi(b.z), 1e-6f));
;         r1[2] = bf_lo(a.w) * __builtin_amdgcn_rcpf(fmaxf(bf_lo(b.w), 1e-6f)); r1[3] = bf_hi(a.w) * __builtin_amdgcn_rcpf(fmaxf(bf_hi(b.w), 1e-6f));
;         acc[ai][bj][m][0] *= r0; acc[ai][bj][m][1] *= r1;
;     }
;     __device__ __forceinline__ void mid(f32x4 (&acc)[2][2][4][2], const Unit& u, int seg, int wr, int wc, int fr, int fq) const {
;         asm volatile("" : "+v"(fr), "+v"(fq));
;         const int row0 = u.pm * BM + wr * 64 + fr, col0 = u.pn * BM + wc * 32 + 8 * fq;
;         u32x4 ga[4][2], gb[4][2], ha[4][2], hb[4][2];
; #pragma unroll
;         for (int m = 0; m < 4; ++m) { const bf16_t* gp = gate + (size_t)(row0 + m * 16) * ldg + seg * DM + col0;
; #pragma unroll
;             for (int bj = 0; bj < 2; ++bj) { ga[m][bj] = *(const u32x4*)(gp + bj * HALF); gb[m][bj] = *(const u32x4*)(gp + DM + bj * HALF); } }
; #pragma unroll
;         for (int m = 0; m < 4; ++m) {
; #pragma unroll
;             for (int bj = 0; bj < 2; ++bj) seam_mul(acc, 0, m, bj, ga[m][bj], gb[m][bj]);
;             const bf16_t* gp = gate + (size_t)(row0 + HALF + m * 16) * ldg + seg * DM + col0;
; #pragma unroll
;             for (int bj = 0; bj < 2; ++bj) { ha[m][bj] = *(const u32x4*)(gp + bj * HALF); hb[m][bj] = *(const u32x4*)(gp + DM + bj * HALF); } }
; #pragma unroll
;         for (int m = 0; m < 4; ++m)
; #pragma unroll
;             for (int bj = 0; bj < 2; ++bj) seam_mul(acc, 1, m, bj, ha[m][bj], hb[m][bj]);
	v_lshlrev_b32_e32 v96, 16, v188
	v_lshlrev_b32_e32 v150, 16, v151
	v_and_b32_e32 v151, 0xffff0000, v151
	v_lshlrev_b32_e32 v134, 16, v135
	v_and_b32_e32 v135, 0xffff0000, v135
	v_pk_mul_f32 v[64:65], v[64:65], v[136:137]
	v_add_co_u32_e32 v136, vcc, s33, v98
	v_max_f32_e32 v96, v96, v96
	v_pk_mul_f32 v[150:151], v[154:155], v[150:151]
	v_pk_mul_f32 v[144:145], v[144:145], v[228:229]
	v_pk_mul_f32 v[134:135], v[138:139], v[134:135]
	v_addc_co_u32_e32 v137, vcc, 0, v99, vcc
	v_max_f32_e32 v96, 0x358637bd, v96
	v_pk_mul_f32 v[88:89], v[88:89], v[160:161]
	v_pk_mul_f32 v[84:85], v[84:85], v[156:157]
	v_pk_mul_f32 v[82:83], v[82:83], v[150:151]
	global_load_dwordx4 v[156:159], v[148:149], off
	global_load_dwordx4 v[160:163], v[152:153], off
	s_nop 0
	global_load_dwordx4 v[148:151], v[148:149], off offset:256
	s_nop 0
	global_load_dwordx4 v[152:155], v[152:153], off offset:256
	v_pk_mul_f32 v[72:73], v[72:73], v[144:145]
	v_pk_mul_f32 v[68:69], v[68:69], v[140:141]
	v_pk_mul_f32 v[66:67], v[66:67], v[134:135]
	global_load_dwordx4 v[140:143], v[98:99], off
	global_load_dwordx4 v[144:147], v[136:137], off
	global_load_dwordx4 v[132:135], v[98:99], off offset:256
	s_nop 0
	global_load_dwordx4 v[136:139], v[136:137], off offset:256
	v_rcp_f32_e32 v98, v96
	v_and_b32_e32 v96, 0xffff0000, v188
	v_max_f32_e32 v96, v96, v96
	v_max_f32_e32 v96, 0x358637bd, v96
	v_rcp_f32_e32 v99, v96
	v_lshlrev_b32_e32 v96, 16, v189
	v_max_f32_e32 v96, v96, v96
	v_max_f32_e32 v96, 0x358637bd, v96
	v_rcp_f32_e32 v188, v96
	v_and_b32_e32 v96, 0xffff0000, v189
	v_max_f32_e32 v96, v96, v96
	v_max_f32_e32 v96, 0x358637bd, v96
	v_rcp_f32_e32 v189, v96
	v_lshlrev_b32_e32 v96, 16, v190
	v_max_f32_e32 v96, v96, v96
	v_lshlrev_b32_e32 v216, 16, v180
	v_and_b32_e32 v217, 0xffff0000, v180
	v_lshlrev_b32_e32 v180, 16, v181
	v_and_b32_e32 v181, 0xffff0000, v181
	v_max_f32_e32 v96, 0x358637bd, v96
	v_pk_mul_f32 v[180:181], v[188:189], v[180:181]
	v_rcp_f32_e32 v188, v96
	v_and_b32_e32 v96, 0xffff0000, v190
	v_max_f32_e32 v96, v96, v96
	v_max_f32_e32 v96, 0x358637bd, v96
	v_rcp_f32_e32 v189, v96
	v_lshlrev_b32_e32 v96, 16, v191
	v_max_f32_e32 v96, v96, v96
	v_max_f32_e32 v96, 0x358637bd, v96
	v_rcp_f32_e32 v190, v96
	v_and_b32_e32 v96, 0xffff0000, v191
	v_max_f32_e32 v96, v96, v96
	v_max_f32_e32 v96, 0x358637bd, v96
	v_rcp_f32_e32 v191, v96
	s_waitcnt vmcnt(12)
	v_lshlrev_b32_e32 v96, 16, v172
	v_max_f32_e32 v96, v96, v96
	v_pk_mul_f32 v[98:99], v[98:99], v[216:217]
	v_max_f32_e32 v96, 0x358637bd, v96
	v_pk_mul_f32 v[60:61], v[60:61], v[98:99]
	v_rcp_f32_e32 v98, v96
	v_and_b32_e32 v96, 0xffff0000, v172
	v_max_f32_e32 v96, v96, v96
	v_max_f32_e32 v96, 0x358637bd, v96
	v_rcp_f32_e32 v99, v96
	v_lshlrev_b32_e32 v96, 16, v173
	v_max_f32_e32 v96, v96, v96
	v_max_f32_e32 v96, 0x358637bd, v96
	v_rcp_f32_e32 v172, v96
	v_and_b32_e32 v96, 0xffff0000, v173
	v_max_f32_e32 v96, v96, v96
	v_max_f32_e32 v96, 0x358637bd, v96
	v_rcp_f32_e32 v173, v96
	v_lshlrev_b32_e32 v96, 16, v174
	v_max_f32_e32 v96, v96, v96
	v_pk_mul_f32 v[62:63], v[62:63], v[180:181]
	v_lshlrev_b32_e32 v180, 16, v164
	v_and_b32_e32 v181, 0xffff0000, v164
	v_lshlrev_b32_e32 v164, 16, v165
	v_and_b32_e32 v165, 0xffff0000, v165
	v_max_f32_e32 v96, 0x358637bd, v96
	v_pk_mul_f32 v[164:165], v[172:173], v[164:165]
	v_rcp_f32_e32 v172, v96
	v_and_b32_e32 v96, 0xffff0000, v174
	v_max_f32_e32 v96, v96, v96
	v_max_f32_e32 v96, 0x358637bd, v96
	v_rcp_f32_e32 v173, v96
	v_lshlrev_b32_e32 v96, 16, v175
	v_max_f32_e32 v96, v96, v96
	v_max_f32_e32 v96, 0x358637bd, v96
	v_rcp_f32_e32 v174, v96
	v_and_b32_e32 v96, 0xffff0000, v175
	v_max_f32_e32 v96, v96, v96
	v_max_f32_e32 v96, 0x358637bd, v96
	v_rcp_f32_e32 v175, v96
	s_waitcnt vmcnt(10)
	v_lshlrev_b32_e32 v96, 16, v192
	v_max_f32_e32 v96, v96, v96
	v_pk_mul_f32 v[98:99], v[98:99], v[180:181]
	v_max_f32_e32 v96, 0x358637bd, v96
	v_pk_mul_f32 v[52:53], v[52:53], v[98:99]
	v_rcp_f32_e32 v98, v96
	v_and_b32_e32 v96, 0xffff0000, v192
	v_max_f32_e32 v96, v96, v96
	v_max_f32_e32 v96, 0x358637bd, v96
	v_rcp_f32_e32 v99, v96
	v_lshlrev_b32_e32 v96, 16, v193
	v_max_f32_e32 v96, v96, v96
	v_pk_mul_f32 v[54:55], v[54:55], v[164:165]
	v_lshlrev_b32_e32 v164, 16, v184
	v_and_b32_e32 v165, 0xffff0000, v184
	v_max_f32_e32 v96, 0x358637bd, v96
	v_pk_mul_f32 v[98:99], v[98:99], v[164:165]
	v_rcp_f32_e32 v164, v96
	v_and_b32_e32 v96, 0xffff0000, v193
	v_max_f32_e32 v96, v96, v96
	v_max_f32_e32 v96, 0x358637bd, v96
	v_rcp_f32_e32 v165, v96
	v_lshlrev_b32_e32 v180, 16, v166
	v_and_b32_e32 v181, 0xffff0000, v166
	v_lshlrev_b32_e32 v166, 16, v167
	v_and_b32_e32 v167, 0xffff0000, v167
	v_lshlrev_b32_e32 v96, 16, v194
	v_pk_mul_f32 v[166:167], v[174:175], v[166:167]
	v_max_f32_e32 v96, v96, v96
	v_pk_mul_f32 v[50:51], v[50:51], v[166:167]
	v_lshlrev_b32_e32 v166, 16, v185
	v_and_b32_e32 v167, 0xffff0000, v185
	v_max_f32_e32 v96, 0x358637bd, v96
	v_pk_mul_f32 v[164:165], v[164:165], v[166:167]
	v_rcp_f32_e32 v166, v96
	v_and_b32_e32 v96, 0xffff0000, v194
	v_max_f32_e32 v96, v96, v96
	v_max_f32_e32 v96, 0x358637bd, v96
	v_rcp_f32_e32 v167, v96
	v_lshlrev_b32_e32 v96, 16, v195
	v_pk_mul_f32 v[172:173], v[172:173], v[180:181]
	v_max_f32_e32 v96, v96, v96
	v_pk_mul_f32 v[48:49], v[48:49], v[172:173]
	v_lshlrev_b32_e32 v172, 16, v186
	v_and_b32_e32 v173, 0xffff0000, v186
	v_max_f32_e32 v96, 0x358637bd, v96
	v_pk_mul_f32 v[166:167], v[166:167], v[172:173]
	v_rcp_f32_e32 v172, v96
	v_and_b32_e32 v96, 0xffff0000, v195
	v_max_f32_e32 v96, v96, v96
	v_max_f32_e32 v96, 0x358637bd, v96
	v_rcp_f32_e32 v173, v96
	s_waitcnt vmcnt(8)
; __device__ __forceinline__ float bf_lo(unsigned w) { return __uint_as_float(w << 16); }
; __device__ __forceinline__ float bf_hi(unsigned w) { return __uint_as_float(w & 0xffff0000u); }
;     __device__ __forceinline__ void seam_mul(f32x4 (&acc)[2][2][4][2], int ai, int m, int bj, const u32x4 a, const u32x4 b) const {
;         f32x4 r0, r1;
;         r0[0] = bf_lo(a.x) * __builtin_amdgcn_rcpf(fmaxf(bf_lo(b.x), 1e-6f)); r0[1] = bf_hi(a.x) * __builtin_amdgcn_rcpf(fmaxf(bf_hi(b.x), 1e-6f));
;         r0[2] = bf_lo(a.y) * __builtin_amdgcn_rcpf(fmaxf(bf_lo(b.y), 1e-6f)); r0[3] = bf_hi(a.y) * __builtin_amdgcn_rcpf(fmaxf(bf_hi(b.y), 1e-6f));
;         r1[0] = bf_lo(a.z) * __builtin_amdgcn_rcpf(fmaxf(bf_lo(b.z), 1e-6f)); r1[1] = bf_hi(a.z) * __builtin_amdgcn_rcpf(fmaxf(bf_hi(b.z), 1e-6f));
;         r1[2] = bf_lo(a.w) * __builtin_amdgcn_rcpf(fmaxf(bf_lo(b.w), 1e-6f)); r1[3] = bf_hi(a.w) * __builtin_amdgcn_rcpf(fmaxf(bf_hi(b.w), 1e-6f));
;         acc[ai][bj][m][0] *= r0; acc[ai][bj][m][1] *= r1;
;     __device__ __forceinline__ void mid(f32x4 (&acc)[2][2][4][2], const Unit& u, int seg, int wr, int wc, int fr, int fq) const {
;     ...
; #pragma unroll
;         for (int m = 0; m < 4; ++m)
; #pragma unroll
;             for (int bj = 0; bj < 2; ++bj) seam_mul(acc, 1, m, bj, ha[m][bj], hb[m][bj]);
	v_lshlrev_b32_e32 v96, 16, v176
	v_max_f32_e32 v96, v96, v96
	v_max_f32_e32 v96, 0x358637bd, v96
	v_pk_mul_f32 v[44:45], v[44:45], v[98:99]
	v_rcp_f32_e32 v98, v96
	v_and_b32_e32 v96, 0xffff0000, v176
	v_max_f32_e32 v96, v96, v96
	v_max_f32_e32 v96, 0x358637bd, v96
	v_rcp_f32_e32 v99, v96
	v_lshlrev_b32_e32 v96, 16, v177
	v_max_f32_e32 v96, v96, v96
	v_pk_mul_f32 v[46:47], v[46:47], v[164:165]
	v_lshlrev_b32_e32 v164, 16, v168
	v_and_b32_e32 v165, 0xffff0000, v168
	v_max_f32_e32 v96, 0x358637bd, v96
	v_pk_mul_f32 v[98:99], v[98:99], v[164:165]
	v_rcp_f32_e32 v164, v96
	v_and_b32_e32 v96, 0xffff0000, v177
	v_max_f32_e32 v96, v96, v96
	v_max_f32_e32 v96, 0x358637bd, v96
	v_rcp_f32_e32 v165, v96
	v_lshlrev_b32_e32 v96, 16, v178
	v_max_f32_e32 v96, v96, v96
	v_pk_mul_f32 v[40:41], v[40:41], v[166:167]
	v_lshlrev_b32_e32 v166, 16, v169
	v_and_b32_e32 v167, 0xffff0000, v169
	v_max_f32_e32 v96, 0x358637bd, v96
	v_pk_mul_f32 v[164:165], v[164:165], v[166:167]
	v_rcp_f32_e32 v166, v96
	v_and_b32_e32 v96, 0xffff0000, v178
	v_max_f32_e32 v96, v96, v96
	v_max_f32_e32 v96, 0x358637bd, v96
	v_rcp_f32_e32 v167, v96
	v_lshlrev_b32_e32 v96, 16, v179
	v_max_f32_e32 v96, v96, v96
	v_lshlrev_b32_e32 v168, 16, v170
	v_and_b32_e32 v169, 0xffff0000, v170
	v_max_f32_e32 v96, 0x358637bd, v96
	v_pk_mul_f32 v[166:167], v[166:167], v[168:169]
	v_rcp_f32_e32 v168, v96
	v_and_b32_e32 v96, 0xffff0000, v179
	v_max_f32_e32 v96, v96, v96
	v_max_f32_e32 v96, 0x358637bd, v96
	v_rcp_f32_e32 v169, v96
	s_waitcnt vmcnt(6)
	v_lshlrev_b32_e32 v96, 16, v160
	v_max_f32_e32 v96, v96, v96
	v_max_f32_e32 v96, 0x358637bd, v96
	v_pk_mul_f32 v[36:37], v[36:37], v[98:99]
	v_rcp_f32_e32 v98, v96
	v_and_b32_e32 v96, 0xffff0000, v160
	v_max_f32_e32 v96, v96, v96
	v_max_f32_e32 v96, 0x358637bd, v96
	v_rcp_f32_e32 v99, v96
	v_lshlrev_b32_e32 v96, 16, v161
	v_max_f32_e32 v96, v96, v96
	v_max_f32_e32 v96, 0x358637bd, v96
	v_rcp_f32_e32 v160, v96
	v_and_b32_e32 v96, 0xffff0000, v161
	v_max_f32_e32 v96, v96, v96
	v_max_f32_e32 v96, 0x358637bd, v96
	v_rcp_f32_e32 v161, v96
	v_lshlrev_b32_e32 v96, 16, v162
	v_max_f32_e32 v96, v96, v96
	v_pk_mul_f32 v[38:39], v[38:39], v[164:165]
	v_lshlrev_b32_e32 v164, 16, v156
	v_and_b32_e32 v165, 0xffff0000, v156
	v_lshlrev_b32_e32 v156, 16, v157
	v_and_b32_e32 v157, 0xffff0000, v157
	v_max_f32_e32 v96, 0x358637bd, v96
	v_pk_mul_f32 v[156:157], v[160:161], v[156:157]
	v_rcp_f32_e32 v160, v96
	v_and_b32_e32 v96, 0xffff0000, v162
	v_max_f32_e32 v96, v96, v96
	v_max_f32_e32 v96, 0x358637bd, v96
	v_rcp_f32_e32 v161, v96
	v_lshlrev_b32_e32 v96, 16, v163
	v_max_f32_e32 v96, v96, v96
	v_max_f32_e32 v96, 0x358637bd, v96
	v_rcp_f32_e32 v162, v96
	v_and_b32_e32 v96, 0xffff0000, v163
	v_max_f32_e32 v96, v96, v96
	v_max_f32_e32 v96, 0x358637bd, v96
	v_rcp_f32_e32 v163, v96
	s_waitcnt vmcnt(4)
	v_lshlrev_b32_e32 v96, 16, v152
	v_max_f32_e32 v96, v96, v96
	v_pk_mul_f32 v[98:99], v[98:99], v[164:165]
	v_max_f32_e32 v96, 0x358637bd, v96
	v_pk_mul_f32 v[28:29], v[28:29], v[98:99]
	v_rcp_f32_e32 v98, v96
	v_and_b32_e32 v96, 0xffff0000, v152
	v_max_f32_e32 v96, v96, v96
	v_max_f32_e32 v96, 0x358637bd, v96
	v_rcp_f32_e32 v99, v96
	v_lshlrev_b32_e32 v96, 16, v153
	v_max_f32_e32 v96, v96, v96
	v_max_f32_e32 v96, 0x358637bd, v96
	v_rcp_f32_e32 v152, v96
	v_and_b32_e32 v96, 0xffff0000, v153
	v_max_f32_e32 v96, v96, v96
	v_max_f32_e32 v96, 0x358637bd, v96
	v_rcp_f32_e32 v153, v96
	v_lshlrev_b32_e32 v96, 16, v154
	v_max_f32_e32 v96, v96, v96
	v_pk_mul_f32 v[30:31], v[30:31], v[156:157]
	v_lshlrev_b32_e32 v156, 16, v148
	v_and_b32_e32 v157, 0xffff0000, v148
	v_lshlrev_b32_e32 v148, 16, v149
	v_and_b32_e32 v149, 0xffff0000, v149
	v_max_f32_e32 v96, 0x358637bd, v96
	v_pk_mul_f32 v[148:149], v[152:153], v[148:149]
	v_rcp_f32_e32 v152, v96
	v_and_b32_e32 v96, 0xffff0000, v154
	v_max_f32_e32 v96, v96, v96
	v_max_f32_e32 v96, 0x358637bd, v96
	v_rcp_f32_e32 v153, v96
	v_lshlrev_b32_e32 v96, 16, v155
	v_max_f32_e32 v96, v96, v96
	v_max_f32_e32 v96, 0x358637bd, v96
	v_rcp_f32_e32 v154, v96
	v_and_b32_e32 v96, 0xffff0000, v155
	v_max_f32_e32 v96, v96, v96
	v_max_f32_e32 v96, 0x358637bd, v96
	v_rcp_f32_e32 v155, v96
	s_waitcnt vmcnt(2)
; __device__ __forceinline__ float bf_lo(unsigned w) { return __uint_as_float(w << 16); }
; __device__ __forceinline__ float bf_hi(unsigned w) { return __uint_as_float(w & 0xffff0000u); }
;     __device__ __forceinline__ void seam_mul(f32x4 (&acc)[2][2][4][2], int ai, int m, int bj, const u32x4 a, const u32x4 b) const {
;         f32x4 r0, r1;
;         r0[0] = bf_lo(a.x) * __builtin_amdgcn_rcpf(fmaxf(bf_lo(b.x), 1e-6f)); r0[1] = bf_hi(a.x) * __builtin_amdgcn_rcpf(fmaxf(bf_hi(b.x), 1e-6f));
;         r0[2] = bf_lo(a.y) * __builtin_amdgcn_rcpf(fmaxf(bf_lo(b.y), 1e-6f)); r0[3] = bf_hi(a.y) * __builtin_amdgcn_rcpf(fmaxf(bf_hi(b.y), 1e-6f));
;         r1[0] = bf_lo(a.z) * __builtin_amdgcn_rcpf(fmaxf(bf_lo(b.z), 1e-6f)); r1[1] = bf_hi(a.z) * __builtin_amdgcn_rcpf(fmaxf(bf_hi(b.z), 1e-6f));
;         r1[2] = bf_lo(a.w) * __builtin_amdgcn_rcpf(fmaxf(bf_lo(b.w), 1e-6f)); r1[3] = bf_hi(a.w) * __builtin_amdgcn_rcpf(fmaxf(bf_hi(b.w), 1e-6f));
;         acc[ai][bj][m][0] *= r0; acc[ai][bj][m][1] *= r1;
;     }
;     __device__ __forceinline__ void mid(f32x4 (&acc)[2][2][4][2], const Unit& u, int seg, int wr, int wc, int fr, int fq) const {
;         asm volatile("" : "+v"(fr), "+v"(fq));
;         const int row0 = u.pm * BM + wr * 64 + fr, col0 = u.pn * BM + wc * 32 + 8 * fq;
;         u32x4 ga[4][2], gb[4][2], ha[4][2], hb[4][2];
; #pragma unroll
;         for (int m = 0; m < 4; ++m) { const bf16_t* gp = gate + (size_t)(row0 + m * 16) * ldg + seg * DM + col0;
; #pragma unroll
;             for (int bj = 0; bj < 2; ++bj) { ga[m][bj] = *(const u32x4*)(gp + bj * HALF); gb[m][bj] = *(const u32x4*)(gp + DM + bj * HALF); } }
; #pragma unroll
;         for (int m = 0; m < 4; ++m) {
; #pragma unroll
;             for (int bj = 0; bj < 2; ++bj) seam_mul(acc, 0, m, bj, ga[m][bj], gb[m][bj]);
;             const bf16_t* gp = gate + (size_t)(row0 + HALF + m * 16) * ldg + seg * DM + col0;
; #pragma unroll
;             for (int bj = 0; bj < 2; ++bj) { ha[m][bj] = *(const u32x4*)(gp + bj * HALF); hb[m][bj] = *(const u32x4*)(gp + DM + bj * HALF); } }
; #pragma unroll
;         for (int m = 0; m < 4; ++m)
; #pragma unroll
;             for (int bj = 0; bj < 2; ++bj) seam_mul(acc, 1, m, bj, ha[m][bj], hb[m][bj]);
	v_lshlrev_b32_e32 v96, 16, v144
	v_max_f32_e32 v96, v96, v96
	v_pk_mul_f32 v[98:99], v[98:99], v[156:157]
	v_max_f32_e32 v96, 0x358637bd, v96
	v_pk_mul_f32 v[20:21], v[20:21], v[98:99]
	v_rcp_f32_e32 v98, v96
	v_and_b32_e32 v96, 0xffff0000, v144
	v_max_f32_e32 v96, v96, v96
	v_max_f32_e32 v96, 0x358637bd, v96
	v_rcp_f32_e32 v99, v96
	v_lshlrev_b32_e32 v96, 16, v145
	v_max_f32_e32 v96, v96, v96
	v_max_f32_e32 v96, 0x358637bd, v96
	v_rcp_f32_e32 v144, v96
	v_and_b32_e32 v96, 0xffff0000, v145
	v_max_f32_e32 v96, v96, v96
	v_max_f32_e32 v96, 0x358637bd, v96
	v_rcp_f32_e32 v145, v96
	v_lshlrev_b32_e32 v96, 16, v146
	v_max_f32_e32 v96, v96, v96
	v_pk_mul_f32 v[22:23], v[22:23], v[148:149]
	v_lshlrev_b32_e32 v148, 16, v140
	v_and_b32_e32 v149, 0xffff0000, v140
	v_lshlrev_b32_e32 v140, 16, v141
	v_and_b32_e32 v141, 0xffff0000, v141
	v_max_f32_e32 v96, 0x358637bd, v96
	v_pk_mul_f32 v[140:141], v[144:145], v[140:141]
	v_rcp_f32_e32 v144, v96
	v_and_b32_e32 v96, 0xffff0000, v146
	v_max_f32_e32 v96, v96, v96
	v_max_f32_e32 v96, 0x358637bd, v96
	v_rcp_f32_e32 v145, v96
	v_lshlrev_b32_e32 v96, 16, v147
	v_max_f32_e32 v96, v96, v96
	v_max_f32_e32 v96, 0x358637bd, v96
	v_rcp_f32_e32 v146, v96
	v_and_b32_e32 v96, 0xffff0000, v147
	v_max_f32_e32 v96, v96, v96
	v_max_f32_e32 v96, 0x358637bd, v96
	v_rcp_f32_e32 v147, v96
	s_waitcnt vmcnt(0)
	v_lshlrev_b32_e32 v96, 16, v136
	v_max_f32_e32 v96, v96, v96
	v_pk_mul_f32 v[98:99], v[98:99], v[148:149]
	v_max_f32_e32 v96, 0x358637bd, v96
	v_pk_mul_f32 v[12:13], v[12:13], v[98:99]
	v_rcp_f32_e32 v98, v96
	v_and_b32_e32 v96, 0xffff0000, v136
	v_max_f32_e32 v96, v96, v96
	v_max_f32_e32 v96, 0x358637bd, v96
	v_rcp_f32_e32 v99, v96
	v_lshlrev_b32_e32 v96, 16, v137
	v_max_f32_e32 v96, v96, v96
	v_max_f32_e32 v96, 0x358637bd, v96
	v_rcp_f32_e32 v136, v96
	v_and_b32_e32 v96, 0xffff0000, v137
	v_max_f32_e32 v96, v96, v96
	v_max_f32_e32 v96, 0x358637bd, v96
	v_rcp_f32_e32 v137, v96
	v_lshlrev_b32_e32 v96, 16, v138
	v_max_f32_e32 v96, v96, v96
	v_pk_mul_f32 v[14:15], v[14:15], v[140:141]
	v_lshlrev_b32_e32 v140, 16, v132
	v_and_b32_e32 v141, 0xffff0000, v132
	v_lshlrev_b32_e32 v132, 16, v133
	v_and_b32_e32 v133, 0xffff0000, v133
	v_max_f32_e32 v96, 0x358637bd, v96
	v_pk_mul_f32 v[132:133], v[136:137], v[132:133]
	v_rcp_f32_e32 v136, v96
	v_and_b32_e32 v96, 0xffff0000, v138
	v_max_f32_e32 v96, v96, v96
	v_max_f32_e32 v96, 0x358637bd, v96
	v_rcp_f32_e32 v137, v96
	v_lshlrev_b32_e32 v96, 16, v139
	v_max_f32_e32 v96, v96, v96
	v_max_f32_e32 v96, 0x358637bd, v96
	v_rcp_f32_e32 v138, v96
	v_and_b32_e32 v96, 0xffff0000, v139
	v_max_f32_e32 v96, v96, v96
	v_max_f32_e32 v96, 0x358637bd, v96
	v_rcp_f32_e32 v139, v96
	v_lshlrev_b32_e32 v216, 16, v182
	v_and_b32_e32 v217, 0xffff0000, v182
	v_lshlrev_b32_e32 v182, 16, v183
	v_and_b32_e32 v183, 0xffff0000, v183
	v_lshlrev_b32_e32 v174, 16, v187
	v_and_b32_e32 v175, 0xffff0000, v187
	v_lshlrev_b32_e32 v170, 16, v171
	v_and_b32_e32 v171, 0xffff0000, v171
	v_lshlrev_b32_e32 v164, 16, v158
	v_and_b32_e32 v165, 0xffff0000, v158
	v_lshlrev_b32_e32 v158, 16, v159
	v_and_b32_e32 v159, 0xffff0000, v159
	v_lshlrev_b32_e32 v156, 16, v150
	v_and_b32_e32 v157, 0xffff0000, v150
	v_lshlrev_b32_e32 v150, 16, v151
	v_and_b32_e32 v151, 0xffff0000, v151
	v_lshlrev_b32_e32 v148, 16, v142
	v_and_b32_e32 v149, 0xffff0000, v142
	v_lshlrev_b32_e32 v142, 16, v143
	v_and_b32_e32 v143, 0xffff0000, v143
	v_pk_mul_f32 v[98:99], v[98:99], v[140:141]
	v_lshlrev_b32_e32 v140, 16, v134
	v_and_b32_e32 v141, 0xffff0000, v134
	v_lshlrev_b32_e32 v134, 16, v135
	v_and_b32_e32 v135, 0xffff0000, v135
	v_pk_mul_f32 v[188:189], v[188:189], v[216:217]
	v_pk_mul_f32 v[182:183], v[190:191], v[182:183]
	v_pk_mul_f32 v[172:173], v[172:173], v[174:175]
	v_pk_mul_f32 v[168:169], v[168:169], v[170:171]
	v_pk_mul_f32 v[160:161], v[160:161], v[164:165]
	v_pk_mul_f32 v[158:159], v[162:163], v[158:159]
	v_pk_mul_f32 v[152:153], v[152:153], v[156:157]
	v_pk_mul_f32 v[150:151], v[154:155], v[150:151]
	v_pk_mul_f32 v[144:145], v[144:145], v[148:149]
	v_pk_mul_f32 v[142:143], v[146:147], v[142:143]
	v_pk_mul_f32 v[136:137], v[136:137], v[140:141]
	v_pk_mul_f32 v[134:135], v[138:139], v[134:135]
	v_pk_mul_f32 v[76:77], v[76:77], v[226:227]
	v_pk_mul_f32 v[58:59], v[58:59], v[182:183]
	v_pk_mul_f32 v[56:57], v[56:57], v[188:189]
	v_pk_mul_f32 v[42:43], v[42:43], v[172:173]
	v_pk_mul_f32 v[34:35], v[34:35], v[168:169]
	v_pk_mul_f32 v[32:33], v[32:33], v[166:167]
	v_pk_mul_f32 v[26:27], v[26:27], v[158:159]
	v_pk_mul_f32 v[24:25], v[24:25], v[160:161]
	v_pk_mul_f32 v[18:19], v[18:19], v[150:151]
	v_pk_mul_f32 v[16:17], v[16:17], v[152:153]
	v_pk_mul_f32 v[10:11], v[10:11], v[142:143]
	v_pk_mul_f32 v[8:9], v[8:9], v[144:145]
	v_pk_mul_f32 v[6:7], v[6:7], v[132:133]
	v_pk_mul_f32 v[4:5], v[4:5], v[98:99]
	v_pk_mul_f32 v[2:3], v[2:3], v[134:135]
	v_pk_mul_f32 v[0:1], v[0:1], v[136:137]
	s_and_b64 vcc, exec, s[18:19]
	s_cbranch_vccz .Lmid_nb2
	s_barrier
.Lmid_nb2:
.LBB0_713:
	s_add_i32 s16, s70, 2
	s_add_u32 s54, s54, 0x100
	s_addc_u32 s55, s55, 0
	s_cmp_gt_u32 s70, 61
	s_cbranch_scc1 .LBB0_715
	s_mov_b32 s70, s16
	s_branch .LBB0_707

; __global__ void __launch_bounds__(NWAVES * 64, 2) mega_fwd(Args args) {
	.amdhsa_kernel _Z8mega_fwd4Args
		.amdhsa_group_segment_fixed_size 0
		.amdhsa_private_segment_fixed_size 0
		.amdhsa_kernarg_size 432
		.amdhsa_user_sgpr_count 2
		.amdhsa_user_sgpr_dispatch_ptr 0
		.amdhsa_user_sgpr_queue_ptr 0
		.amdhsa_user_sgpr_kernarg_segment_ptr 1
		.amdhsa_user_sgpr_dispatch_id 0
		.amdhsa_user_sgpr_kernarg_preload_length 0
		.amdhsa_user_sgpr_kernarg_preload_offset 0
		.amdhsa_user_sgpr_private_segment_size 0
		.amdhsa_uses_dynamic_stack 0
		.amdhsa_enable_private_segment 0
		.amdhsa_system_sgpr_workgroup_id_x 1
		.amdhsa_system_sgpr_workgroup_id_y 0
		.amdhsa_system_sgpr_workgroup_id_z 0
		.amdhsa_system_sgpr_workgroup_info 0
		.amdhsa_system_vgpr_workitem_id 0
		.amdhsa_next_free_vgpr 256
		.amdhsa_next_free_sgpr 100
		.amdhsa_accum_offset 256
		.amdhsa_reserve_vcc 1
		.amdhsa_float_round_mode_32 0
		.amdhsa_float_round_mode_16_64 0
		.amdhsa_float_denorm_mode_32 3
		.amdhsa_float_denorm_mode_16_64 3
		.amdhsa_dx10_clamp 1
		.amdhsa_ieee_mode 1
		.amdhsa_fp16_overflow 0
		.amdhsa_tg_split 0
		.amdhsa_exception_fp_ieee_invalid_op 0
		.amdhsa_exception_fp_denorm_src 0
		.amdhsa_exception_fp_ieee_div_zero 0
		.amdhsa_exception_fp_ieee_overflow 0
		.amdhsa_exception_fp_ieee_underflow 0
		.amdhsa_exception_fp_ieee_inexact 0
		.amdhsa_exception_int_div_zero 0
	.end_amdhsa_kernel

; __global__ void __launch_bounds__(NWAVES * 64, 2) mega_fwd(Args args) {
amdhsa.kernels:
  - .agpr_count:     0
    .args:
      - .offset:         0
        .size:           176
        .value_kind:     by_value
      - .offset:         176
        .size:           4
        .value_kind:     hidden_block_count_x
      - .offset:         180
        .size:           4
        .value_kind:     hidden_block_count_y
      - .offset:         184
        .size:           4
        .value_kind:     hidden_block_count_z
      - .offset:         188
        .size:           2
        .value_kind:     hidden_group_size_x
      - .offset:         190
        .size:           2
        .value_kind:     hidden_group_size_y
      - .offset:         192
        .size:           2
        .value_kind:     hidden_group_size_z
      - .offset:         194
        .size:           2
        .value_kind:     hidden_remainder_x
      - .offset:         196
        .size:           2
        .value_kind:     hidden_remainder_y
      - .offset:         198
        .size:           2
        .value_kind:     hidden_remainder_z
      - .offset:         216
        .size:           8
        .value_kind:     hidden_global_offset_x
      - .offset:         224
        .size:           8
        .value_kind:     hidden_global_offset_y
      - .offset:         232
        .size:           8
        .value_kind:     hidden_global_offset_z
      - .offset:         240
        .size:           2
        .value_kind:     hidden_grid_dims
      - .offset:         296
        .size:           4
        .value_kind:     hidden_dynamic_lds_size
    .group_segment_fixed_size: 0
    .kernarg_segment_align: 8
    .kernarg_segment_size: 432
    .language:       OpenCL C
    .language_version:
      - 2
      - 0
    .max_flat_workgroup_size: 512
    .name:           _Z8mega_fwd4Args
    .private_segment_fixed_size: 0
    .sgpr_count:     106
    .sgpr_spill_count: 27
    .symbol:         _Z8mega_fwd4Args.kd
    .uniform_work_group_size: 1
    .uses_dynamic_stack: false
    .vgpr_count:     256
    .vgpr_spill_count: 0
    .wavefront_size: 64
